# attention task queue: next ticket's atomic issued when the current task is accepted (round trip overlaps the task) on v52
# baseline (speedup 1.0000x reference)
.LBB0_194:
	s_mov_b32 s100, 0
	s_xor_b64 s[42:43], s[8:9], -1
	v_cndmask_b32_e64 v0, 0, 1, s[6:7]
	v_readlane_b32 s8, v255, 37
	v_lshlrev_b32_e32 v160, 2, v0
	v_readlane_b32 s9, v255, 38
	s_and_b64 s[6:7], s[6:7], exec
	s_cselect_b32 s26, 0x180, 0
	v_lshl_add_u64 v[192:193], s[8:9], 0, v[160:161]
	s_branch .LBB0_197

.LBB0_197:
	s_and_saveexec_b64 s[6:7], s[36:37]
	s_cbranch_execz .LBB0_201
	s_mov_b64 s[10:11], exec
	v_mbcnt_lo_u32_b32 v0, s10, 0
	v_mbcnt_hi_u32_b32 v0, s11, v0
	v_cmp_eq_u32_e32 vcc, 0, v0
	s_and_saveexec_b64 s[8:9], vcc
	s_cbranch_execz .LBB0_200
	s_cmp_lg_u32 s100, 0
	s_cbranch_scc1 .Lda_tk_have
	s_bcnt1_i32_b64 s4, s[10:11]
	v_mov_b32_e32 v1, s4
	global_atomic_add v1, v[192:193], v1, off offset:256 sc0
	s_branch .LBB0_200
.Lda_tk_have:
	s_waitcnt vmcnt(0)
	v_mov_b32_e32 v1, v235

.LBB0_201:
	s_or_b64 exec, exec, s[6:7]
	v_mov_b32_e32 v0, s97
	s_waitcnt lgkmcnt(0)
	s_barrier
	ds_read_b32 v0, v0
	s_movk_i32 s6, 0x17f
	s_waitcnt lgkmcnt(0)
	s_barrier
	v_cmp_lt_u32_e32 vcc, s6, v0
	v_readfirstlane_b32 s4, v0
	s_mov_b64 s[6:7], -1
	s_cbranch_vccnz .LBB0_196
	s_and_saveexec_b64 s[98:99], s[36:37]
	s_cbranch_execz .Lda_tk_pf
	v_mov_b32_e32 v235, 1
	global_atomic_add v235, v[192:193], v235, off offset:256 sc0
	s_mov_b32 s100, 1
.Lda_tk_pf:
	s_or_b64 exec, exec, s[98:99]
	s_add_i32 s4, s4, s26
	s_and_b32 s6, s4, 0xffff
	s_mul_i32 s6, s6, 0xaaab
	s_lshr_b32 s8, s6, 20
	s_mul_i32 s6, s8, 24
	s_sub_i32 s9, s4, s6
	s_mul_i32 s4, s9, 0xab
	s_lshl_b32 s7, s8, 7
	s_bfe_u32 s4, s4, 0x6000a
	v_subrev_u32_e32 v26, s7, v199
	s_mul_i32 s6, s4, 6
	v_add_u32_e32 v212, 0xf80, v26
	s_sub_i32 s6, s9, s6
	v_or_b32_e32 v213, v212, v181
	s_lshl_b32 s7, s4, 12
	v_add_lshl_u32 v160, v213, s7, 11
	s_and_b32 s10, s6, 0xff
	v_lshl_add_u64 v[0:1], s[64:65], 0, v[160:161]
	s_lshl_b32 s4, s10, 8
	v_lshl_add_u64 v[0:1], v[0:1], 0, s[4:5]
	v_lshl_add_u64 v[0:1], v[176:177], 1, v[0:1]
	v_mov_b32_e32 v189, v161
	v_lshl_add_u64 v[24:25], v[0:1], 0, v[188:189]
	v_add_u32_e32 v2, s7, v200
	v_mov_b64_e32 v[0:1], s[30:31]
	v_mad_i64_i32 v[0:1], s[6:7], v2, s35, v[0:1]
	v_lshl_add_u64 v[0:1], v[0:1], 0, s[4:5]
	s_lshl_b32 s4, s9, 7
	v_mov_b32_e32 v191, v161
	s_and_b32 s4, s4, 0xff80
	v_lshl_add_u64 v[194:195], v[0:1], 0, v[190:191]
	v_lshl_add_u64 v[0:1], s[4:5], 0, v[178:179]
	s_mov_b32 s4, 0xc000
	v_lshlrev_b64 v[0:1], 13, v[0:1]
	v_add_co_u32_e32 v8, vcc, s4, v194
	v_lshl_add_u64 v[196:197], v[182:183], 0, v[0:1]
	s_nop 0
	v_addc_co_u32_e32 v9, vcc, 0, v195, vcc
	s_mov_b32 s4, 0x80000
	v_add_co_u32_e32 v12, vcc, s4, v196
	s_mov_b32 s4, 0x18000
	s_nop 0
	v_addc_co_u32_e32 v13, vcc, 0, v197, vcc
	global_load_dwordx4 v[0:3], v[194:195], off
	global_load_dwordx4 v[4:7], v[196:197], off
	s_nop 0
	global_load_dwordx4 v[8:11], v[8:9], off
	s_nop 0
	global_load_dwordx4 v[12:15], v[12:13], off
	v_add_co_u32_e32 v16, vcc, s4, v194
	s_mov_b32 s4, 0x24000
	s_nop 0
	v_addc_co_u32_e32 v17, vcc, 0, v195, vcc
	v_add_co_u32_e32 v20, vcc, s4, v194
	s_mov_b32 s24, 1
	s_nop 0
	v_addc_co_u32_e32 v21, vcc, 0, v195, vcc
	global_load_dwordx4 v[16:19], v[16:17], off
	s_nop 0
	global_load_dwordx4 v[20:23], v[20:21], off
	s_nop 0
	global_load_dwordx4 v[128:131], v[24:25], off
	global_load_dwordx4 v[132:135], v[24:25], off offset:32
	global_load_dwordx4 v[136:139], v[24:25], off offset:64
	global_load_dwordx4 v[140:143], v[24:25], off offset:96
	v_add_u32_e32 v189, 0xc800, v211
	v_add_u32_e32 v191, 0xf000, v211
	s_lshl_b32 s27, s10, 7
	s_lshl_b32 s22, s8, 1
	s_waitcnt vmcnt(9)
	ds_write_b128 v175, v[0:3]
	s_waitcnt vmcnt(7)
	ds_write_b128 v175, v[8:11] offset:8704
	ds_write2_b64 v189, v[4:5], v[6:7] offset0:128 offset1:130
	s_waitcnt vmcnt(6)
	ds_write2_b64 v191, v[12:13], v[14:15] offset1:2
	s_waitcnt vmcnt(5)
	ds_write_b128 v175, v[16:19] offset:17408
	s_waitcnt vmcnt(4)
	ds_write_b128 v175, v[20:23] offset:26112
	s_waitcnt lgkmcnt(0)
	s_barrier
	s_setprio 1
	v_add_u32_e32 v8, v203, v204
	ds_read_b128 v[0:3], v8
	ds_read_b128 v[4:7], v8 offset:32
	s_mov_b32 s4, s5
	s_mov_b32 s6, s5
	s_mov_b32 s7, s5
	s_waitcnt vmcnt(3) lgkmcnt(1)
	v_mfma_f32_32x32x16_bf16 v[64:79], v[0:3], v[128:131], 0
	s_mov_b32 s8, s5
	s_mov_b32 s9, s5
	s_mov_b32 s10, s5
	s_mov_b32 s11, s5
	s_mov_b32 s12, s5
	s_mov_b32 s13, s5
	s_mov_b32 s14, s5
	s_waitcnt vmcnt(2) lgkmcnt(0)
	v_mfma_f32_32x32x16_bf16 v[64:79], v[4:7], v[132:135], v[64:79]
	ds_read_b128 v[0:3], v8 offset:64
	ds_read_b128 v[4:7], v8 offset:96
	s_mov_b32 s15, s5
	s_mov_b32 s16, s5
	s_mov_b32 s17, s5
	s_mov_b32 s18, s5
	s_mov_b32 s19, s5
	s_waitcnt vmcnt(1) lgkmcnt(1)
	v_mfma_f32_32x32x16_bf16 v[64:79], v[0:3], v[136:139], v[64:79]
	s_waitcnt vmcnt(0) lgkmcnt(0)
	v_mfma_f32_32x32x16_bf16 v[64:79], v[4:7], v[140:143], v[64:79]
	ds_read_b128 v[0:3], v8 offset:8704
	ds_read_b128 v[4:7], v8 offset:8736
	ds_read_b128 v[16:19], v8 offset:8800
	s_waitcnt lgkmcnt(2)
	v_mfma_f32_32x32x16_bf16 v[80:95], v[0:3], v[128:131], 0
	ds_read_b128 v[0:3], v8 offset:8768
	s_waitcnt lgkmcnt(2)
	v_mfma_f32_32x32x16_bf16 v[80:95], v[4:7], v[132:135], v[80:95]
	s_waitcnt lgkmcnt(0)
	v_mfma_f32_32x32x16_bf16 v[80:95], v[0:3], v[136:139], v[80:95]
	v_mov_b64_e32 v[0:1], s[4:5]
	v_mov_b64_e32 v[2:3], s[6:7]
	v_mov_b64_e32 v[4:5], s[8:9]
	v_mov_b64_e32 v[6:7], s[10:11]
	v_mov_b64_e32 v[8:9], s[12:13]
	v_mov_b64_e32 v[10:11], s[14:15]
	v_mov_b64_e32 v[12:13], s[16:17]
	v_mfma_f32_32x32x16_bf16 v[80:95], v[16:19], v[140:143], v[80:95]
	v_mov_b64_e32 v[14:15], s[18:19]
	s_sub_i32 s12, 64, s22
	s_setprio 0
	v_add_u32_e32 v214, 0xf9f, v26
	v_mov_b64_e32 v[30:31], v[14:15]
	v_mov_b64_e32 v[46:47], v[14:15]
	v_mov_b64_e32 v[62:63], v[14:15]
	s_mov_b32 s13, 63
	s_sub_i32 s14, 63, s22
	s_mov_b32 s16, 2
	v_mov_b32_e32 v170, 0xff800000
	v_mov_b32_e32 v215, 0
	s_mov_b32 s15, 3
	v_mov_b64_e32 v[28:29], v[12:13]
	v_mov_b64_e32 v[26:27], v[10:11]
	v_mov_b64_e32 v[24:25], v[8:9]
	v_mov_b64_e32 v[22:23], v[6:7]
	v_mov_b64_e32 v[20:21], v[4:5]
	v_mov_b64_e32 v[18:19], v[2:3]
	v_mov_b64_e32 v[16:17], v[0:1]
	v_mov_b64_e32 v[44:45], v[12:13]
	v_mov_b64_e32 v[42:43], v[10:11]
	v_mov_b64_e32 v[40:41], v[8:9]
	v_mov_b64_e32 v[38:39], v[6:7]
	v_mov_b64_e32 v[36:37], v[4:5]
	v_mov_b64_e32 v[34:35], v[2:3]
	v_mov_b64_e32 v[32:33], v[0:1]
	v_mov_b64_e32 v[60:61], v[12:13]
	v_mov_b64_e32 v[58:59], v[10:11]
	v_mov_b64_e32 v[56:57], v[8:9]
	v_mov_b64_e32 v[54:55], v[6:7]
	v_mov_b64_e32 v[52:53], v[4:5]
	v_mov_b64_e32 v[50:51], v[2:3]
	v_mov_b64_e32 v[48:49], v[0:1]
	s_branch .LBB0_205
